# v132 with nt hint removed from norm-phase x loads
# speedup vs baseline: 1.0158x; 1.0099x over previous
.LBB0_443:
	v_readlane_b32 s56, v254, 4
	v_min_i32_e32 v6, s6, v66
	v_readlane_b32 s71, v254, 19
	v_add_u32_e32 v0, 0xffff8000, v6
	v_ashrrev_i32_e32 v2, 31, v6
	v_cmp_gt_i32_e32 vcc, s40, v6
	v_mov_b32_e32 v4, s55
	v_readlane_b32 s70, v254, 18
	v_mov_b32_e32 v5, s71
	v_cndmask_b32_e32 v3, 0, v2, vcc
	v_cndmask_b32_e32 v2, v0, v6, vcc
	v_cndmask_b32_e32 v5, v4, v5, vcc
	v_mov_b32_e32 v4, s54
	v_mov_b32_e32 v7, s70
	v_cndmask_b32_e32 v4, v4, v7, vcc
	v_lshlrev_b64 v[2:3], 12, v[2:3]
	v_lshl_add_u64 v[2:3], v[4:5], 0, v[2:3]
	v_mov_b32_e32 v85, v1
	v_lshl_add_u64 v[2:3], v[2:3], 0, v[84:85]
	global_load_dwordx4 v[62:65], v[2:3], off
	global_load_dwordx4 v[50:53], v[2:3], off offset:1024
	global_load_dwordx4 v[46:49], v[2:3], off offset:2048
	global_load_dwordx4 v[30:33], v[2:3], off offset:3072
	v_cmp_lt_i32_e32 vcc, s14, v6
	v_readlane_b32 s57, v254, 5
	v_readlane_b32 s58, v254, 6
	v_readlane_b32 s59, v254, 7
	v_readlane_b32 s60, v254, 8
	v_readlane_b32 s61, v254, 9
	v_readlane_b32 s62, v254, 10
	v_readlane_b32 s63, v254, 11
	v_readlane_b32 s64, v254, 12
	v_readlane_b32 s65, v254, 13
	v_readlane_b32 s66, v254, 14
	v_readlane_b32 s67, v254, 15
	v_readlane_b32 s68, v254, 16
	v_readlane_b32 s69, v254, 17
	s_and_saveexec_b64 s[36:37], vcc
	s_cbranch_execz .LBB0_445
	v_readlane_b32 s10, v253, 18
	v_lshlrev_b64 v[2:3], 12, v[0:1]
	v_readlane_b32 s11, v253, 19
	v_mov_b32_e32 v87, v1
	v_mov_b32_e32 v89, v1
	v_lshl_add_u64 v[10:11], s[10:11], 0, v[2:3]
	s_mov_b64 s[10:11], 0x800000
	v_lshl_add_u64 v[8:9], v[10:11], 0, s[10:11]
	s_mov_b64 s[10:11], 0x1000000
	v_lshl_add_u64 v[6:7], v[10:11], 0, s[10:11]
	s_mov_b64 s[10:11], 0x1800000
	v_lshl_add_u64 v[4:5], v[10:11], 0, s[10:11]
	v_lshl_add_u64 v[10:11], v[10:11], 0, v[84:85]
	v_lshl_add_u64 v[8:9], v[8:9], 0, v[84:85]
	v_lshl_add_u64 v[6:7], v[6:7], 0, v[84:85]
	v_lshl_add_u64 v[4:5], v[4:5], 0, v[84:85]
	v_mov_b32_e32 v91, v1
	v_lshl_add_u64 v[2:3], v[78:79], 0, v[2:3]
	global_load_dwordx4 v[114:117], v[10:11], off
	global_load_dwordx4 v[118:121], v[8:9], off
	global_load_dwordx4 v[122:125], v[6:7], off
	global_load_dwordx4 v[126:129], v[4:5], off
	global_load_dwordx4 v[200:203], v[68:69], off
	global_load_dwordx4 v[130:133], v[10:11], off offset:1024
	global_load_dwordx4 v[134:137], v[8:9], off offset:1024
	global_load_dwordx4 v[138:141], v[6:7], off offset:1024
	global_load_dwordx4 v[142:145], v[4:5], off offset:1024
	global_load_dwordx4 v[204:207], v[70:71], off
	global_load_dwordx4 v[146:149], v[10:11], off offset:2048
	global_load_dwordx4 v[150:153], v[8:9], off offset:2048
	global_load_dwordx4 v[176:179], v[6:7], off offset:2048
	global_load_dwordx4 v[180:183], v[4:5], off offset:2048
	global_load_dwordx4 v[208:211], v[72:73], off
	global_load_dwordx4 v[184:187], v[10:11], off offset:3072
	global_load_dwordx4 v[188:191], v[8:9], off offset:3072
	global_load_dwordx4 v[192:195], v[6:7], off offset:3072
	global_load_dwordx4 v[196:199], v[4:5], off offset:3072
	global_load_dwordx4 v[20:23], v[74:75], off
	s_waitcnt vmcnt(15)
	v_pk_add_f32 v[114:115], v[114:115], v[118:119]
	v_pk_add_f32 v[116:117], v[116:117], v[120:121]
	v_pk_add_f32 v[114:115], v[114:115], v[122:123]
	v_pk_add_f32 v[116:117], v[116:117], v[124:125]
	v_pk_add_f32 v[114:115], v[114:115], v[126:127]
	v_pk_add_f32 v[116:117], v[116:117], v[128:129]
	v_pk_fma_f32 v[62:63], v[114:115], v[200:201], v[62:63]
	v_pk_fma_f32 v[64:65], v[116:117], v[202:203], v[64:65]
	global_store_dwordx4 v[2:3], v[62:65], off
	s_waitcnt vmcnt(11)
	v_pk_add_f32 v[130:131], v[130:131], v[134:135]
	v_pk_add_f32 v[132:133], v[132:133], v[136:137]
	v_pk_add_f32 v[130:131], v[130:131], v[138:139]
	v_pk_add_f32 v[132:133], v[132:133], v[140:141]
	v_pk_add_f32 v[130:131], v[130:131], v[142:143]
	v_pk_add_f32 v[132:133], v[132:133], v[144:145]
	v_pk_fma_f32 v[50:51], v[130:131], v[204:205], v[50:51]
	v_pk_fma_f32 v[52:53], v[132:133], v[206:207], v[52:53]
	global_store_dwordx4 v[2:3], v[50:53], off offset:1024
	s_waitcnt vmcnt(7)
	v_pk_add_f32 v[146:147], v[146:147], v[150:151]
	v_pk_add_f32 v[148:149], v[148:149], v[152:153]
	v_pk_add_f32 v[146:147], v[146:147], v[176:177]
	v_pk_add_f32 v[148:149], v[148:149], v[178:179]
	v_pk_add_f32 v[146:147], v[146:147], v[180:181]
	v_pk_add_f32 v[148:149], v[148:149], v[182:183]
	v_pk_fma_f32 v[46:47], v[146:147], v[208:209], v[46:47]
	v_pk_fma_f32 v[48:49], v[148:149], v[210:211], v[48:49]
	global_store_dwordx4 v[2:3], v[46:49], off offset:2048
	s_waitcnt vmcnt(3)
	v_pk_add_f32 v[184:185], v[184:185], v[188:189]
	v_pk_add_f32 v[186:187], v[186:187], v[190:191]
	v_pk_add_f32 v[184:185], v[184:185], v[192:193]
	v_pk_add_f32 v[186:187], v[186:187], v[194:195]
	v_pk_add_f32 v[184:185], v[184:185], v[196:197]
	v_pk_add_f32 v[186:187], v[186:187], v[198:199]
	v_pk_fma_f32 v[30:31], v[184:185], v[20:21], v[30:31]
	v_pk_fma_f32 v[32:33], v[186:187], v[22:23], v[32:33]
	global_store_dwordx4 v[2:3], v[30:33], off offset:3072
.LBB0_445:
	s_or_b64 exec, exec, s[36:37]
	v_add_u32_e32 v96, s5, v66
	v_readlane_b32 s56, v254, 4
	v_min_i32_e32 v6, s6, v96
	v_readlane_b32 s71, v254, 19
	v_ashrrev_i32_e32 v2, 31, v6
	v_add_u32_e32 v0, 0xffff8000, v6
	v_cmp_gt_i32_e32 vcc, s40, v6
	v_mov_b32_e32 v4, s55
	v_readlane_b32 s70, v254, 18
	v_mov_b32_e32 v5, s71
	v_cndmask_b32_e32 v3, 0, v2, vcc
	v_cndmask_b32_e32 v2, v0, v6, vcc
	v_cndmask_b32_e32 v5, v4, v5, vcc
	v_mov_b32_e32 v4, s54
	v_mov_b32_e32 v7, s70
	v_cndmask_b32_e32 v4, v4, v7, vcc
	v_lshlrev_b64 v[2:3], 12, v[2:3]
	v_lshl_add_u64 v[2:3], v[4:5], 0, v[2:3]
	v_lshl_add_u64 v[2:3], v[2:3], 0, v[84:85]
	global_load_dwordx4 v[58:61], v[2:3], off
	global_load_dwordx4 v[42:45], v[2:3], off offset:1024
	global_load_dwordx4 v[38:41], v[2:3], off offset:2048
	global_load_dwordx4 v[34:37], v[2:3], off offset:3072
	v_cmp_lt_i32_e32 vcc, s14, v6
	v_cmp_gt_i32_e64 s[10:11], s4, v96
	s_and_b64 vcc, vcc, s[10:11]
	v_readlane_b32 s57, v254, 5
	v_readlane_b32 s58, v254, 6
	v_readlane_b32 s59, v254, 7
	v_readlane_b32 s60, v254, 8
	v_readlane_b32 s61, v254, 9
	v_readlane_b32 s62, v254, 10
	v_readlane_b32 s63, v254, 11
	v_readlane_b32 s64, v254, 12
	v_readlane_b32 s65, v254, 13
	v_readlane_b32 s66, v254, 14
	v_readlane_b32 s67, v254, 15
	v_readlane_b32 s68, v254, 16
	v_readlane_b32 s69, v254, 17
	s_and_saveexec_b64 s[36:37], vcc
	s_cbranch_execz .LBB0_455
	v_readlane_b32 s10, v253, 18
	v_lshlrev_b64 v[2:3], 12, v[0:1]
	v_readlane_b32 s11, v253, 19
	v_mov_b32_e32 v85, v1
	v_cmp_gt_i32_e32 vcc, s4, v96
	v_lshl_add_u64 v[10:11], s[10:11], 0, v[2:3]
	s_mov_b64 s[10:11], 0x800000
	v_lshl_add_u64 v[8:9], v[10:11], 0, s[10:11]
	s_mov_b64 s[10:11], 0x1000000
	v_lshl_add_u64 v[6:7], v[10:11], 0, s[10:11]
	s_mov_b64 s[10:11], 0x1800000
	v_lshl_add_u64 v[4:5], v[10:11], 0, s[10:11]
	v_lshl_add_u64 v[10:11], v[10:11], 0, v[84:85]
	v_lshl_add_u64 v[16:17], v[8:9], 0, v[84:85]
	global_load_dwordx4 v[12:15], v[10:11], off
	v_lshl_add_u64 v[2:3], s[54:55], 0, v[2:3]
	global_load_dwordx4 v[16:19], v[16:17], off
	s_waitcnt vmcnt(0)
	v_pk_add_f32 v[16:17], v[12:13], v[16:17]
	v_lshl_add_u64 v[12:13], v[6:7], 0, v[84:85]
	v_pk_add_f32 v[18:19], v[14:15], v[18:19]
	global_load_dwordx4 v[12:15], v[12:13], off
	s_waitcnt vmcnt(0)
	v_pk_add_f32 v[16:17], v[16:17], v[12:13]
	v_lshl_add_u64 v[12:13], v[4:5], 0, v[84:85]
	v_pk_add_f32 v[18:19], v[18:19], v[14:15]
	global_load_dwordx4 v[12:15], v[12:13], off
	s_waitcnt vmcnt(0)
	v_pk_add_f32 v[18:19], v[18:19], v[14:15]
	v_pk_add_f32 v[16:17], v[16:17], v[12:13]
	global_load_dwordx4 v[12:15], v[68:69], off
	s_waitcnt vmcnt(0)
	v_pk_fma_f32 v[60:61], v[18:19], v[14:15], v[60:61]
	v_pk_fma_f32 v[58:59], v[16:17], v[12:13], v[58:59]
	s_and_saveexec_b64 s[38:39], vcc
	s_cbranch_execz .LBB0_448
	v_lshl_add_u64 v[12:13], v[2:3], 0, v[84:85]
	global_store_dwordx4 v[12:13], v[58:61], off

.LBB0_455:
	s_or_b64 exec, exec, s[36:37]
	v_add_u32_e32 v94, s7, v66
	v_readlane_b32 s56, v254, 4
	v_min_i32_e32 v6, s6, v94
	v_readlane_b32 s71, v254, 19
	v_ashrrev_i32_e32 v2, 31, v6
	v_add_u32_e32 v0, 0xffff8000, v6
	v_cmp_gt_i32_e32 vcc, s40, v6
	v_mov_b32_e32 v4, s55
	v_readlane_b32 s70, v254, 18
	v_mov_b32_e32 v5, s71
	v_cndmask_b32_e32 v3, 0, v2, vcc
	v_cndmask_b32_e32 v2, v0, v6, vcc
	v_cndmask_b32_e32 v5, v4, v5, vcc
	v_mov_b32_e32 v4, s54
	v_mov_b32_e32 v7, s70
	v_cndmask_b32_e32 v4, v4, v7, vcc
	v_lshlrev_b64 v[2:3], 12, v[2:3]
	v_lshl_add_u64 v[2:3], v[4:5], 0, v[2:3]
	v_mov_b32_e32 v85, v1
	v_lshl_add_u64 v[2:3], v[2:3], 0, v[84:85]
	global_load_dwordx4 v[54:57], v[2:3], off
	global_load_dwordx4 v[26:29], v[2:3], off offset:1024
	global_load_dwordx4 v[18:21], v[2:3], off offset:2048
	global_load_dwordx4 v[14:17], v[2:3], off offset:3072
	v_cmp_lt_i32_e32 vcc, s14, v6
	v_cmp_gt_i32_e64 s[10:11], s4, v94
	s_and_b64 vcc, vcc, s[10:11]
	v_readlane_b32 s57, v254, 5
	v_readlane_b32 s58, v254, 6
	v_readlane_b32 s59, v254, 7
	v_readlane_b32 s60, v254, 8
	v_readlane_b32 s61, v254, 9
	v_readlane_b32 s62, v254, 10
	v_readlane_b32 s63, v254, 11
	v_readlane_b32 s64, v254, 12
	v_readlane_b32 s65, v254, 13
	v_readlane_b32 s66, v254, 14
	v_readlane_b32 s67, v254, 15
	v_readlane_b32 s68, v254, 16
	v_readlane_b32 s69, v254, 17
	s_and_saveexec_b64 s[36:37], vcc
	s_cbranch_execz .LBB0_465
	v_readlane_b32 s10, v253, 18
	v_lshlrev_b64 v[2:3], 12, v[0:1]
	v_readlane_b32 s11, v253, 19
	v_cmp_gt_i32_e32 vcc, s4, v94
	s_nop 0
	v_lshl_add_u64 v[10:11], s[10:11], 0, v[2:3]
	s_mov_b64 s[10:11], 0x800000
	v_lshl_add_u64 v[8:9], v[10:11], 0, s[10:11]
	s_mov_b64 s[10:11], 0x1000000
	v_lshl_add_u64 v[6:7], v[10:11], 0, s[10:11]
	s_mov_b64 s[10:11], 0x1800000
	v_lshl_add_u64 v[4:5], v[10:11], 0, s[10:11]
	v_lshl_add_u64 v[10:11], v[10:11], 0, v[84:85]
	v_lshl_add_u64 v[12:13], v[8:9], 0, v[84:85]
	global_load_dwordx4 v[22:25], v[10:11], off
	global_load_dwordx4 v[98:101], v[12:13], off
	v_lshl_add_u64 v[2:3], s[54:55], 0, v[2:3]
	s_waitcnt vmcnt(0)
	v_pk_add_f32 v[92:93], v[22:23], v[98:99]
	v_lshl_add_u64 v[22:23], v[6:7], 0, v[84:85]
	v_pk_add_f32 v[12:13], v[24:25], v[100:101]
	global_load_dwordx4 v[22:25], v[22:23], off
	s_waitcnt vmcnt(0)
	v_pk_add_f32 v[92:93], v[92:93], v[22:23]
	v_lshl_add_u64 v[22:23], v[4:5], 0, v[84:85]
	v_pk_add_f32 v[12:13], v[12:13], v[24:25]
	global_load_dwordx4 v[22:25], v[22:23], off
	s_waitcnt vmcnt(0)
	v_pk_add_f32 v[12:13], v[12:13], v[24:25]
	v_pk_add_f32 v[92:93], v[92:93], v[22:23]
	global_load_dwordx4 v[22:25], v[68:69], off
	s_waitcnt vmcnt(0)
	v_pk_fma_f32 v[56:57], v[12:13], v[24:25], v[56:57]
	v_pk_fma_f32 v[54:55], v[92:93], v[22:23], v[54:55]
	s_and_saveexec_b64 s[38:39], vcc
	s_cbranch_execz .LBB0_458
	v_mov_b32_e32 v85, v1
	v_lshl_add_u64 v[12:13], v[2:3], 0, v[84:85]
	global_store_dwordx4 v[12:13], v[54:57], off

.LBB0_465:
	s_or_b64 exec, exec, s[36:37]
	v_add_u32_e32 v92, s8, v66
	v_readlane_b32 s56, v254, 4
	v_min_i32_e32 v67, s6, v92
	v_readlane_b32 s71, v254, 19
	v_ashrrev_i32_e32 v2, 31, v67
	v_add_u32_e32 v0, 0xffff8000, v67
	v_cmp_gt_i32_e32 vcc, s40, v67
	v_mov_b32_e32 v4, s55
	v_readlane_b32 s70, v254, 18
	v_mov_b32_e32 v5, s71
	v_cndmask_b32_e32 v3, 0, v2, vcc
	v_cndmask_b32_e32 v2, v0, v67, vcc
	v_cndmask_b32_e32 v5, v4, v5, vcc
	v_mov_b32_e32 v4, s54
	v_mov_b32_e32 v6, s70
	v_cndmask_b32_e32 v4, v4, v6, vcc
	v_lshlrev_b64 v[2:3], 12, v[2:3]
	v_lshl_add_u64 v[2:3], v[4:5], 0, v[2:3]
	v_mov_b32_e32 v85, v1
	v_lshl_add_u64 v[2:3], v[2:3], 0, v[84:85]
	global_load_dwordx4 v[22:25], v[2:3], off
	global_load_dwordx4 v[10:13], v[2:3], off offset:1024
	global_load_dwordx4 v[6:9], v[2:3], off offset:2048
	s_nop 0
	global_load_dwordx4 v[2:5], v[2:3], off offset:3072
	v_cmp_lt_i32_e32 vcc, s14, v67
	v_cmp_gt_i32_e64 s[10:11], s4, v92
	s_and_b64 vcc, vcc, s[10:11]
	v_readlane_b32 s57, v254, 5
	v_readlane_b32 s58, v254, 6
	v_readlane_b32 s59, v254, 7
	v_readlane_b32 s60, v254, 8
	v_readlane_b32 s61, v254, 9
	v_readlane_b32 s62, v254, 10
	v_readlane_b32 s63, v254, 11
	v_readlane_b32 s64, v254, 12
	v_readlane_b32 s65, v254, 13
	v_readlane_b32 s66, v254, 14
	v_readlane_b32 s67, v254, 15
	v_readlane_b32 s68, v254, 16
	v_readlane_b32 s69, v254, 17
	s_and_saveexec_b64 s[36:37], vcc
	s_cbranch_execz .LBB0_475
	v_readlane_b32 s10, v253, 18
	v_lshlrev_b64 v[98:99], 12, v[0:1]
	v_readlane_b32 s11, v253, 19
	v_cmp_gt_i32_e32 vcc, s4, v92
	s_nop 0
	v_lshl_add_u64 v[106:107], s[10:11], 0, v[98:99]
	s_mov_b64 s[10:11], 0x800000
	v_lshl_add_u64 v[104:105], v[106:107], 0, s[10:11]
	s_mov_b64 s[10:11], 0x1000000
	v_lshl_add_u64 v[102:103], v[106:107], 0, s[10:11]
	s_mov_b64 s[10:11], 0x1800000
	v_lshl_add_u64 v[100:101], v[106:107], 0, s[10:11]
	v_lshl_add_u64 v[106:107], v[106:107], 0, v[84:85]
	v_lshl_add_u64 v[118:119], v[104:105], 0, v[84:85]
	global_load_dwordx4 v[114:117], v[106:107], off
	v_lshl_add_u64 v[98:99], s[54:55], 0, v[98:99]
	global_load_dwordx4 v[118:121], v[118:119], off
	s_waitcnt vmcnt(0)
	v_pk_add_f32 v[118:119], v[114:115], v[118:119]
	v_lshl_add_u64 v[114:115], v[102:103], 0, v[84:85]
	v_pk_add_f32 v[120:121], v[116:117], v[120:121]
	global_load_dwordx4 v[114:117], v[114:115], off
	s_waitcnt vmcnt(0)
	v_pk_add_f32 v[118:119], v[118:119], v[114:115]
	v_lshl_add_u64 v[114:115], v[100:101], 0, v[84:85]
	v_pk_add_f32 v[120:121], v[120:121], v[116:117]
	global_load_dwordx4 v[114:117], v[114:115], off
	s_waitcnt vmcnt(0)
	v_pk_add_f32 v[120:121], v[120:121], v[116:117]
	v_pk_add_f32 v[118:119], v[118:119], v[114:115]
	global_load_dwordx4 v[114:117], v[68:69], off
	s_waitcnt vmcnt(0)
	v_pk_fma_f32 v[24:25], v[120:121], v[116:117], v[24:25]
	v_pk_fma_f32 v[22:23], v[118:119], v[114:115], v[22:23]
	s_and_saveexec_b64 s[38:39], vcc
	s_cbranch_execz .LBB0_468
	v_mov_b32_e32 v85, v1
	v_lshl_add_u64 v[114:115], v[98:99], 0, v[84:85]
	global_store_dwordx4 v[114:115], v[22:25], off

.LBB0_530:
	v_add_u32_e32 v0, 0xffff8000, v66
	v_cmp_gt_i32_e32 vcc, s40, v66
	v_mov_b32_e32 v4, s55
	v_mov_b32_e32 v5, s48
	v_cndmask_b32_e32 v3, 0, v67, vcc
	v_cndmask_b32_e32 v2, v0, v66, vcc
	v_cndmask_b32_e32 v5, v4, v5, vcc
	v_mov_b32_e32 v4, s54
	v_mov_b32_e32 v6, s49
	v_cndmask_b32_e32 v4, v4, v6, vcc
	v_lshlrev_b64 v[2:3], 12, v[2:3]
	v_lshl_add_u64 v[2:3], v[4:5], 0, v[2:3]
	v_mov_b32_e32 v79, v1
	v_lshl_add_u64 v[2:3], v[2:3], 0, v[78:79]
	global_load_dwordx4 v[38:41], v[2:3], off
	global_load_dwordx4 v[22:25], v[2:3], off offset:1024
	global_load_dwordx4 v[6:9], v[2:3], off offset:2048
	s_nop 0
	global_load_dwordx4 v[2:5], v[2:3], off offset:3072
	v_cmp_lt_i32_e32 vcc, s14, v66
	s_and_b64 s[8:9], s[22:23], vcc
	s_and_saveexec_b64 s[34:35], s[8:9]
	s_cbranch_execz .LBB0_532
	v_readlane_b32 s8, v253, 18
	v_lshlrev_b64 v[34:35], 12, v[0:1]
	v_readlane_b32 s9, v253, 19
	v_mov_b32_e32 v81, v1
	v_lshl_add_u64 v[62:63], v[72:73], 0, v[34:35]
	v_lshl_add_u64 v[10:11], s[8:9], 0, v[34:35]
	s_mov_b64 s[8:9], 0x800000
	v_lshl_add_u64 v[54:55], v[10:11], 0, s[8:9]
	s_mov_b64 s[8:9], 0x1000000
	v_lshl_add_u64 v[56:57], v[10:11], 0, s[8:9]
	s_mov_b64 s[8:9], 0x1800000
	v_lshl_add_u64 v[60:61], v[10:11], 0, v[78:79]
	v_lshl_add_u64 v[14:15], v[54:55], 0, v[78:79]
	v_lshl_add_u64 v[58:59], v[10:11], 0, s[8:9]
	global_load_dwordx4 v[10:13], v[60:61], off
	v_lshl_add_u64 v[18:19], v[56:57], 0, v[78:79]
	global_load_dwordx4 v[14:17], v[14:15], off
	v_lshl_add_u64 v[26:27], v[58:59], 0, v[78:79]
	global_load_dwordx4 v[18:21], v[18:19], off
	s_nop 0
	global_load_dwordx4 v[26:29], v[26:27], off
	s_nop 0
	global_load_dwordx4 v[30:33], v[68:69], off
	global_load_dwordx4 v[34:37], v[60:61], off offset:1024
	v_lshl_add_u64 v[42:43], v[54:55], 0, v[80:81]
	v_lshl_add_u64 v[46:47], v[56:57], 0, v[80:81]
	v_lshl_add_u64 v[50:51], v[58:59], 0, v[80:81]
	global_load_dwordx4 v[42:45], v[42:43], off
	s_nop 0
	global_load_dwordx4 v[46:49], v[46:47], off
	s_nop 0
	global_load_dwordx4 v[50:53], v[50:51], off
	v_mov_b32_e32 v83, v1
	v_mov_b32_e32 v85, v1
	s_waitcnt vmcnt(0)
	v_pk_add_f32 v[12:13], v[12:13], v[16:17]
	v_pk_add_f32 v[10:11], v[10:11], v[14:15]
	v_pk_add_f32 v[12:13], v[12:13], v[20:21]
	v_pk_add_f32 v[10:11], v[10:11], v[18:19]
	v_pk_add_f32 v[12:13], v[12:13], v[28:29]
	v_pk_add_f32 v[10:11], v[10:11], v[26:27]
	v_pk_fma_f32 v[40:41], v[12:13], v[32:33], v[40:41]
	v_pk_fma_f32 v[38:39], v[10:11], v[30:31], v[38:39]
	global_store_dwordx4 v[62:63], v[38:41], off
	global_load_dwordx4 v[10:13], v[68:69], off offset:1024
	v_pk_add_f32 v[36:37], v[36:37], v[44:45]
	v_pk_add_f32 v[34:35], v[34:35], v[42:43]
	v_pk_add_f32 v[36:37], v[36:37], v[48:49]
	v_pk_add_f32 v[34:35], v[34:35], v[46:47]
	global_load_dwordx4 v[14:17], v[60:61], off offset:2048
	v_pk_add_f32 v[36:37], v[36:37], v[52:53]
	v_pk_add_f32 v[34:35], v[34:35], v[50:51]
	v_lshl_add_u64 v[18:19], v[54:55], 0, v[82:83]
	v_lshl_add_u64 v[26:27], v[56:57], 0, v[82:83]
	v_lshl_add_u64 v[30:31], v[58:59], 0, v[82:83]
	global_load_dwordx4 v[18:21], v[18:19], off
	s_nop 0
	global_load_dwordx4 v[26:29], v[26:27], off
	s_nop 0
	global_load_dwordx4 v[30:33], v[30:31], off
	v_lshl_add_u64 v[42:43], v[54:55], 0, v[84:85]
	v_lshl_add_u64 v[46:47], v[56:57], 0, v[84:85]
	v_lshl_add_u64 v[50:51], v[58:59], 0, v[84:85]
	s_waitcnt vmcnt(4)
	v_pk_fma_f32 v[24:25], v[36:37], v[12:13], v[24:25]
	v_pk_fma_f32 v[22:23], v[34:35], v[10:11], v[22:23]
	global_store_dwordx4 v[62:63], v[22:25], off offset:1024
	global_load_dwordx4 v[10:13], v[68:69], off offset:2048
	global_load_dwordx4 v[34:37], v[60:61], off offset:3072
	s_nop 0
	global_load_dwordx4 v[42:45], v[42:43], off
	s_nop 0
	global_load_dwordx4 v[46:49], v[46:47], off
	s_nop 0
	global_load_dwordx4 v[50:53], v[50:51], off
	s_waitcnt vmcnt(8)
	v_pk_add_f32 v[16:17], v[16:17], v[20:21]
	v_pk_add_f32 v[14:15], v[14:15], v[18:19]
	s_waitcnt vmcnt(7)
	v_pk_add_f32 v[16:17], v[16:17], v[28:29]
	v_pk_add_f32 v[14:15], v[14:15], v[26:27]
	s_waitcnt vmcnt(6)
	v_pk_add_f32 v[16:17], v[16:17], v[32:33]
	v_pk_add_f32 v[14:15], v[14:15], v[30:31]
	s_waitcnt vmcnt(4)
	v_pk_fma_f32 v[8:9], v[16:17], v[12:13], v[8:9]
	v_pk_fma_f32 v[6:7], v[14:15], v[10:11], v[6:7]
	global_store_dwordx4 v[62:63], v[6:9], off offset:2048
	global_load_dwordx4 v[10:13], v[68:69], off offset:3072
	s_waitcnt vmcnt(4)
	v_pk_add_f32 v[14:15], v[36:37], v[44:45]
	v_pk_add_f32 v[16:17], v[34:35], v[42:43]
	s_waitcnt vmcnt(3)
	v_pk_add_f32 v[14:15], v[14:15], v[48:49]
	v_pk_add_f32 v[16:17], v[16:17], v[46:47]
	s_waitcnt vmcnt(2)
	v_pk_add_f32 v[14:15], v[14:15], v[52:53]
	v_pk_add_f32 v[16:17], v[16:17], v[50:51]
	s_waitcnt vmcnt(0)
	v_pk_fma_f32 v[4:5], v[14:15], v[12:13], v[4:5]
	v_pk_fma_f32 v[2:3], v[16:17], v[10:11], v[2:3]
	global_store_dwordx4 v[62:63], v[2:5], off offset:3072
.LBB0_532:
	s_or_b64 exec, exec, s[34:35]
	v_add_u32_e32 v86, s4, v66
	v_min_i32_e32 v10, 0x87ff, v86
	v_ashrrev_i32_e32 v11, 31, v10
	v_add_u32_e32 v0, 0xffff8000, v10
	v_cmp_gt_i32_e32 vcc, s40, v86
	v_mov_b32_e32 v12, s55
	v_mov_b32_e32 v13, s48
	v_cndmask_b32_e32 v11, 0, v11, vcc
	v_cndmask_b32_e32 v10, v0, v10, vcc
	v_cndmask_b32_e32 v13, v12, v13, vcc
	v_mov_b32_e32 v12, s54
	v_mov_b32_e32 v14, s49
	v_cndmask_b32_e32 v12, v12, v14, vcc
	v_lshlrev_b64 v[10:11], 12, v[10:11]
	v_lshl_add_u64 v[10:11], v[12:13], 0, v[10:11]
	v_lshl_add_u64 v[10:11], v[10:11], 0, v[78:79]
	global_load_dwordx4 v[34:37], v[10:11], off
	global_load_dwordx4 v[30:33], v[10:11], off offset:1024
	global_load_dwordx4 v[18:21], v[10:11], off offset:2048
	s_nop 0
	global_load_dwordx4 v[10:13], v[10:11], off offset:3072
	v_cmp_lt_i32_e32 vcc, s14, v86
	s_mov_b32 s8, 0x8800
	v_cmp_gt_i32_e64 s[8:9], s8, v86
	s_and_b64 vcc, vcc, s[8:9]
	s_and_b64 s[8:9], s[22:23], vcc
	s_and_saveexec_b64 s[34:35], s[8:9]
	s_cbranch_execz .LBB0_542
	v_readlane_b32 s8, v253, 18
	v_lshlrev_b64 v[14:15], 12, v[0:1]
	v_readlane_b32 s9, v253, 19
	v_mov_b32_e32 v79, v1
	v_cmp_gt_u32_e32 vcc, s15, v86
	v_lshl_add_u64 v[42:43], s[8:9], 0, v[14:15]
	s_mov_b64 s[8:9], 0x800000
	v_lshl_add_u64 v[28:29], v[42:43], 0, s[8:9]
	s_mov_b64 s[8:9], 0x1000000
	v_lshl_add_u64 v[26:27], v[42:43], 0, s[8:9]
	s_mov_b64 s[8:9], 0x1800000
	v_lshl_add_u64 v[16:17], v[42:43], 0, s[8:9]
	v_lshl_add_u64 v[42:43], v[42:43], 0, v[78:79]
	v_lshl_add_u64 v[28:29], v[28:29], 0, v[78:79]
	v_lshl_add_u64 v[26:27], v[26:27], 0, v[78:79]
	v_lshl_add_u64 v[16:17], v[16:17], 0, v[78:79]
	v_lshl_add_u64 v[14:15], s[54:55], 0, v[14:15]
	v_lshl_add_u64 v[44:45], v[14:15], 0, v[78:79]
	global_load_dwordx4 v[118:121], v[42:43], off
	global_load_dwordx4 v[122:125], v[28:29], off
	global_load_dwordx4 v[126:129], v[26:27], off
	global_load_dwordx4 v[130:133], v[16:17], off
	global_load_dwordx4 v[204:207], v[68:69], off
	global_load_dwordx4 v[134:137], v[42:43], off offset:1024
	global_load_dwordx4 v[138:141], v[28:29], off offset:1024
	global_load_dwordx4 v[142:145], v[26:27], off offset:1024
	global_load_dwordx4 v[146:149], v[16:17], off offset:1024
	global_load_dwordx4 v[208:211], v[68:69], off offset:1024
	global_load_dwordx4 v[150:153], v[42:43], off offset:2048
	global_load_dwordx4 v[176:179], v[28:29], off offset:2048
	global_load_dwordx4 v[180:183], v[26:27], off offset:2048
	global_load_dwordx4 v[184:187], v[16:17], off offset:2048
	global_load_dwordx4 v[88:91], v[68:69], off offset:2048
	global_load_dwordx4 v[188:191], v[42:43], off offset:3072
	global_load_dwordx4 v[192:195], v[28:29], off offset:3072
	global_load_dwordx4 v[196:199], v[26:27], off offset:3072
	global_load_dwordx4 v[200:203], v[16:17], off offset:3072
	global_load_dwordx4 v[92:95], v[68:69], off offset:3072
	s_waitcnt vmcnt(15)
	v_pk_add_f32 v[120:121], v[120:121], v[124:125]
	v_pk_add_f32 v[118:119], v[118:119], v[122:123]
	v_pk_add_f32 v[120:121], v[120:121], v[128:129]
	v_pk_add_f32 v[118:119], v[118:119], v[126:127]
	v_pk_add_f32 v[120:121], v[120:121], v[132:133]
	v_pk_add_f32 v[118:119], v[118:119], v[130:131]
	v_pk_fma_f32 v[36:37], v[120:121], v[206:207], v[36:37]
	v_pk_fma_f32 v[34:35], v[118:119], v[204:205], v[34:35]
	s_and_saveexec_b64 s[36:37], vcc
	global_store_dwordx4 v[44:45], v[34:37], off
	s_or_b64 exec, exec, s[36:37]
	s_waitcnt vmcnt(10)
	v_pk_add_f32 v[136:137], v[136:137], v[140:141]
	v_pk_add_f32 v[134:135], v[134:135], v[138:139]
	v_pk_add_f32 v[136:137], v[136:137], v[144:145]
	v_pk_add_f32 v[134:135], v[134:135], v[142:143]
	v_pk_add_f32 v[136:137], v[136:137], v[148:149]
	v_pk_add_f32 v[134:135], v[134:135], v[146:147]
	v_pk_fma_f32 v[32:33], v[136:137], v[210:211], v[32:33]
	v_pk_fma_f32 v[30:31], v[134:135], v[208:209], v[30:31]
	s_and_saveexec_b64 s[36:37], vcc
	global_store_dwordx4 v[44:45], v[30:33], off offset:1024
	s_or_b64 exec, exec, s[36:37]
	s_waitcnt vmcnt(5)
	v_pk_add_f32 v[152:153], v[152:153], v[178:179]
	v_pk_add_f32 v[150:151], v[150:151], v[176:177]
	v_pk_add_f32 v[152:153], v[152:153], v[182:183]
	v_pk_add_f32 v[150:151], v[150:151], v[180:181]
	v_pk_add_f32 v[152:153], v[152:153], v[186:187]
	v_pk_add_f32 v[150:151], v[150:151], v[184:185]
	v_pk_fma_f32 v[20:21], v[152:153], v[90:91], v[20:21]
	v_pk_fma_f32 v[18:19], v[150:151], v[88:89], v[18:19]
	s_and_saveexec_b64 s[36:37], vcc
	global_store_dwordx4 v[44:45], v[18:21], off offset:2048
	s_or_b64 exec, exec, s[36:37]
	s_waitcnt vmcnt(0)
	v_pk_add_f32 v[190:191], v[190:191], v[194:195]
	v_pk_add_f32 v[188:189], v[188:189], v[192:193]
	v_pk_add_f32 v[190:191], v[190:191], v[198:199]
	v_pk_add_f32 v[188:189], v[188:189], v[196:197]
	v_pk_add_f32 v[190:191], v[190:191], v[202:203]
	v_pk_add_f32 v[188:189], v[188:189], v[200:201]
	v_pk_fma_f32 v[12:13], v[190:191], v[94:95], v[12:13]
	v_pk_fma_f32 v[10:11], v[188:189], v[92:93], v[10:11]
	s_and_saveexec_b64 s[36:37], vcc
	global_store_dwordx4 v[44:45], v[10:13], off offset:3072
	s_or_b64 exec, exec, s[36:37]

.LBB0_542:
	s_or_b64 exec, exec, s[34:35]
	v_add_u32_e32 v88, s5, v66
	v_min_i32_e32 v14, 0x87ff, v88
	v_ashrrev_i32_e32 v15, 31, v14
	v_add_u32_e32 v0, 0xffff8000, v14
	v_cmp_gt_i32_e32 vcc, s40, v88
	v_mov_b32_e32 v16, s55
	v_mov_b32_e32 v17, s48
	v_cndmask_b32_e32 v15, 0, v15, vcc
	v_cndmask_b32_e32 v14, v0, v14, vcc
	v_cndmask_b32_e32 v17, v16, v17, vcc
	v_mov_b32_e32 v16, s54
	v_mov_b32_e32 v26, s49
	v_cndmask_b32_e32 v16, v16, v26, vcc
	v_lshlrev_b64 v[14:15], 12, v[14:15]
	v_lshl_add_u64 v[14:15], v[16:17], 0, v[14:15]
	v_mov_b32_e32 v79, v1
	v_lshl_add_u64 v[14:15], v[14:15], 0, v[78:79]
	global_load_dwordx4 v[46:49], v[14:15], off
	global_load_dwordx4 v[42:45], v[14:15], off offset:1024
	global_load_dwordx4 v[26:29], v[14:15], off offset:2048
	s_nop 0
	global_load_dwordx4 v[14:17], v[14:15], off offset:3072
	v_cmp_lt_i32_e32 vcc, s14, v88
	s_mov_b32 s8, 0x8800
	v_cmp_gt_i32_e64 s[8:9], s8, v88
	s_and_b64 vcc, vcc, s[8:9]
	s_and_b64 s[8:9], s[22:23], vcc
	s_and_saveexec_b64 s[34:35], s[8:9]
	s_cbranch_execz .LBB0_552
	v_readlane_b32 s8, v253, 18
	v_lshlrev_b64 v[50:51], 12, v[0:1]
	v_readlane_b32 s9, v253, 19
	v_cmp_gt_u32_e32 vcc, s15, v88
	s_nop 0
	v_lshl_add_u64 v[58:59], s[8:9], 0, v[50:51]
	s_mov_b64 s[8:9], 0x800000
	v_lshl_add_u64 v[56:57], v[58:59], 0, s[8:9]
	s_mov_b64 s[8:9], 0x1000000
	v_lshl_add_u64 v[54:55], v[58:59], 0, s[8:9]
	s_mov_b64 s[8:9], 0x1800000
	v_lshl_add_u64 v[52:53], v[58:59], 0, s[8:9]
	v_lshl_add_u64 v[58:59], v[58:59], 0, v[78:79]
	v_lshl_add_u64 v[64:65], v[56:57], 0, v[78:79]
	global_load_dwordx4 v[60:63], v[58:59], off
	global_load_dwordx4 v[90:93], v[64:65], off
	v_lshl_add_u64 v[50:51], s[54:55], 0, v[50:51]
	s_waitcnt vmcnt(0)
	v_pk_add_f32 v[90:91], v[60:61], v[90:91]
	v_lshl_add_u64 v[60:61], v[54:55], 0, v[78:79]
	v_pk_add_f32 v[64:65], v[62:63], v[92:93]
	global_load_dwordx4 v[60:63], v[60:61], off
	s_waitcnt vmcnt(0)
	v_pk_add_f32 v[90:91], v[90:91], v[60:61]
	v_lshl_add_u64 v[60:61], v[52:53], 0, v[78:79]
	v_pk_add_f32 v[64:65], v[64:65], v[62:63]
	global_load_dwordx4 v[60:63], v[60:61], off
	s_waitcnt vmcnt(0)
	v_pk_add_f32 v[64:65], v[64:65], v[62:63]
	v_pk_add_f32 v[90:91], v[90:91], v[60:61]
	global_load_dwordx4 v[60:63], v[68:69], off
	s_waitcnt vmcnt(0)
	v_pk_fma_f32 v[48:49], v[64:65], v[62:63], v[48:49]
	v_pk_fma_f32 v[46:47], v[90:91], v[60:61], v[46:47]
	s_and_saveexec_b64 s[36:37], vcc
	s_cbranch_execz .LBB0_545
	v_mov_b32_e32 v79, v1
	v_lshl_add_u64 v[60:61], v[50:51], 0, v[78:79]
	global_store_dwordx4 v[60:61], v[46:49], off

.LBB0_552:
	s_or_b64 exec, exec, s[34:35]
	v_add_u32_e32 v90, s6, v66
	v_min_i32_e32 v50, 0x87ff, v90
	v_ashrrev_i32_e32 v51, 31, v50
	v_add_u32_e32 v0, 0xffff8000, v50
	v_cmp_gt_i32_e32 vcc, s40, v90
	v_mov_b32_e32 v52, s55
	v_mov_b32_e32 v53, s48
	v_cndmask_b32_e32 v51, 0, v51, vcc
	v_cndmask_b32_e32 v50, v0, v50, vcc
	v_cndmask_b32_e32 v53, v52, v53, vcc
	v_mov_b32_e32 v52, s54
	v_mov_b32_e32 v54, s49
	v_cndmask_b32_e32 v52, v52, v54, vcc
	v_lshlrev_b64 v[50:51], 12, v[50:51]
	v_lshl_add_u64 v[50:51], v[52:53], 0, v[50:51]
	v_mov_b32_e32 v79, v1
	v_lshl_add_u64 v[50:51], v[50:51], 0, v[78:79]
	global_load_dwordx4 v[62:65], v[50:51], off
	global_load_dwordx4 v[58:61], v[50:51], off offset:1024
	global_load_dwordx4 v[54:57], v[50:51], off offset:2048
	s_nop 0
	global_load_dwordx4 v[50:53], v[50:51], off offset:3072
	v_cmp_lt_i32_e32 vcc, s14, v90
	s_mov_b32 s8, 0x8800
	v_cmp_gt_i32_e64 s[8:9], s8, v90
	s_and_b64 vcc, vcc, s[8:9]
	s_and_b64 s[8:9], s[22:23], vcc
	s_and_saveexec_b64 s[34:35], s[8:9]
	s_cbranch_execz .LBB0_562
	v_readlane_b32 s8, v253, 18
	v_lshlrev_b64 v[92:93], 12, v[0:1]
	v_readlane_b32 s9, v253, 19
	v_cmp_gt_u32_e32 vcc, s15, v90
	s_nop 0
	v_lshl_add_u64 v[100:101], s[8:9], 0, v[92:93]
	s_mov_b64 s[8:9], 0x800000
	v_lshl_add_u64 v[98:99], v[100:101], 0, s[8:9]
	s_mov_b64 s[8:9], 0x1000000
	v_lshl_add_u64 v[96:97], v[100:101], 0, s[8:9]
	s_mov_b64 s[8:9], 0x1800000
	v_lshl_add_u64 v[94:95], v[100:101], 0, s[8:9]
	v_lshl_add_u64 v[100:101], v[100:101], 0, v[78:79]
	v_lshl_add_u64 v[112:113], v[98:99], 0, v[78:79]
	global_load_dwordx4 v[108:111], v[100:101], off
	s_nop 0
	global_load_dwordx4 v[112:115], v[112:113], off
	v_lshl_add_u64 v[116:117], v[96:97], 0, v[78:79]
	global_load_dwordx4 v[116:119], v[116:117], off
	v_lshl_add_u64 v[120:121], v[94:95], 0, v[78:79]
	global_load_dwordx4 v[120:123], v[120:121], off
	s_nop 0
	global_load_dwordx4 v[124:127], v[68:69], off
	v_lshl_add_u64 v[92:93], s[54:55], 0, v[92:93]
	s_waitcnt vmcnt(0)
	v_pk_add_f32 v[110:111], v[110:111], v[114:115]
	v_pk_add_f32 v[108:109], v[108:109], v[112:113]
	v_pk_add_f32 v[110:111], v[110:111], v[118:119]
	v_pk_add_f32 v[108:109], v[108:109], v[116:117]
	v_pk_add_f32 v[110:111], v[110:111], v[122:123]
	v_pk_add_f32 v[108:109], v[108:109], v[120:121]
	v_pk_fma_f32 v[64:65], v[110:111], v[126:127], v[64:65]
	v_pk_fma_f32 v[62:63], v[108:109], v[124:125], v[62:63]
	s_and_saveexec_b64 s[36:37], vcc
	s_cbranch_execz .LBB0_555
	v_mov_b32_e32 v79, v1
	v_lshl_add_u64 v[108:109], v[92:93], 0, v[78:79]
	global_store_dwordx4 v[108:109], v[62:65], off
